# v058 plus mode-3 L2 segment: the two s_nop M0 wait slots now hold that segment's last two ds_read_b128 (no nops left in heavy load segments of mode 3)
# baseline (speedup 1.0000x reference)
; #define PG8_STAGE(bufoff, gbase, voff) do { _Pragma("unroll") for (int _i = 0; _i < 2; ++_i) \
;         __builtin_amdgcn_global_load_lds((const unsigned*)((const char*)(gbase) + (voff)[_i]), (LAS unsigned*)(lds + (bufoff) + ldsw + _i * 8192), 16, 0, 0); } while (0)
; #define PG8_LDA(dst, b, h) do { _Pragma("unroll") for (int m = 0; m < 4; ++m) _Pragma("unroll") for (int k = 0; k < 2; ++k) dst[m][k] = *(const LAS bf16x8*)(lds + PG8_SA(b, h) + aoff + m * 2048 + k * 1024); } while (0)
; #define PG8_LDB(dst, b, h) do { _Pragma("unroll") for (int n = 0; n < 2; ++n) _Pragma("unroll") for (int k = 0; k < 2; ++k) dst[n][k] = *(const LAS bf16x8*)(lds + PG8_SB(b, h) + boff + n * 2048 + k * 1024); } while (0)
; #define PG8_MMA(ai, bj, At, Bt) do { __builtin_amdgcn_s_setprio(1); _Pragma("unroll") for (int m = 0; m < 4; ++m) _Pragma("unroll") for (int n = 0; n < 2; ++n) _Pragma("unroll") for (int k = 0; k < 2; ++k) \
;         acc[ai][bj][m][n] = __builtin_amdgcn_mfma_f32_16x16x32_bf16(Bt[n][k], At[m][k], acc[ai][bj][m][n], 0, 0, 0); __builtin_amdgcn_s_setprio(0); } while (0)
; #define PG8_WAIT_V(n) asm volatile("s_waitcnt vmcnt(" #n ")" ::: "memory")
; #define PG8_WAIT_L(n) asm volatile("s_waitcnt lgkmcnt(" #n ")" ::: "memory")
; template <int MODE, class EpiT, class Sched>
; __device__ __forceinline__ void gemm_phase(LAS unsigned char* lds, const Gemm g, const Sched& S, const EpiT& E) {
;     ...
;         for (int t = 0; t < nt; t += 2) {
;             const bool last = (t == nt - 2);
;             const char* a1 = cA + (size_t)(t + 1) * kstep;
;             const char* a2 = last ? nA : cA + (size_t)(t + 2) * kstep; const char* b2 = last ? nB : cB + (size_t)(t + 2) * kstep;
;             const char* a3 = a2 + kstep; const char* b3 = b2 + kstep;
;             PG8_LDB(B0, 0, 0); PG8_SCHED; PG8_LDA(At, 0, 0); PG8_STAGE(PG8_SA(1, 1), a1 + hstep, voffA);
;             PG8_WAIT_L(8); PG8_BAR; PG8_WAIT_L(0); PG8_MMA(0, 0, At, B0); PG8_BAR; PG8_SCHED;
;             PG8_LDB(B1, 0, 1); PG8_STAGE(PG8_SB(0, 0), b2, voffB);
;             PG8_BAR; PG8_WAIT_L(0); PG8_MMA(0, 1, At, B1); PG8_BAR;
;             PG8_LDA(At, 0, 1); PG8_STAGE(PG8_SA(0, 0), a2, voffA);
;             PG8_BAR; PG8_WAIT_L(0); PG8_MMA(1, 0, At, B0); PG8_BAR; PG8_SCHED;
;             PG8_STAGE(PG8_SB(0, 1), b2 + hstep, voffB);
;             PG8_WAIT_V(6); PG8_BAR; PG8_MMA(1, 1, At, B1); PG8_BAR;
.LBB0_195:
	s_add_i32 vcc_lo, vcc_lo, 2
	ds_read_b128 v[58:61], v249
	ds_read_b128 v[62:65], v249 offset:1024
	ds_read_b128 v[70:73], v249 offset:2048
	ds_read_b128 v[74:77], v249 offset:3072
	s_add_i32 m0, s21, 0xc000
	ds_read_b128 v[138:141], v196
	ds_read_b128 v[142:145], v196 offset:1024
	ds_read_b128 v[146:149], v196 offset:2048
	ds_read_b128 v[150:153], v196 offset:3072
	ds_read_b128 v[162:165], v196 offset:4096
	ds_read_b128 v[166:169], v196 offset:5120
	ds_read_b128 v[170:173], v196 offset:6144
	global_load_lds_dwordx4 v0, s[100:101]
	s_add_i32 m0, s21, 0xe000
	ds_read_b128 v[184:187], v196 offset:7168
	global_load_lds_dwordx4 v174, s[100:101]
	s_waitcnt lgkmcnt(8)
	s_barrier
	s_waitcnt lgkmcnt(0)
	v_mfma_f32_16x16x32_bf16 v[158:161], v[58:61], v[138:141], v[158:161]
	v_mfma_f32_16x16x32_bf16 v[154:157], v[70:73], v[138:141], v[154:157]
	v_mfma_f32_16x16x32_bf16 v[126:129], v[58:61], v[146:149], v[126:129]
	v_mfma_f32_16x16x32_bf16 v[122:125], v[70:73], v[146:149], v[122:125]
	v_mfma_f32_16x16x32_bf16 v[110:113], v[58:61], v[162:165], v[110:113]
	v_mfma_f32_16x16x32_bf16 v[106:109], v[70:73], v[162:165], v[106:109]
	v_mfma_f32_16x16x32_bf16 v[94:97], v[58:61], v[170:173], v[94:97]
	v_mfma_f32_16x16x32_bf16 v[90:93], v[70:73], v[170:173], v[90:93]
	v_mfma_f32_16x16x32_bf16 v[158:161], v[62:65], v[142:145], v[158:161]
	v_mfma_f32_16x16x32_bf16 v[154:157], v[74:77], v[142:145], v[154:157]
	v_mfma_f32_16x16x32_bf16 v[126:129], v[62:65], v[150:153], v[126:129]
	v_mfma_f32_16x16x32_bf16 v[122:125], v[74:77], v[150:153], v[122:125]
	v_mfma_f32_16x16x32_bf16 v[110:113], v[62:65], v[166:169], v[110:113]
	v_mfma_f32_16x16x32_bf16 v[106:109], v[74:77], v[166:169], v[106:109]
	v_mfma_f32_16x16x32_bf16 v[94:97], v[62:65], v[184:187], v[94:97]
	v_mfma_f32_16x16x32_bf16 v[90:93], v[74:77], v[184:187], v[90:93]
	s_barrier
	ds_read_b128 v[188:191], v249 offset:16384
	ds_read_b128 v[220:223], v249 offset:17408
	s_add_i32 m0, s20, 0x10000
	ds_read_b128 v[224:227], v249 offset:18432
	global_load_lds_dwordx4 v0, s[52:53]
	s_add_i32 m0, s20, 0x12000
	ds_read_b128 v[228:231], v249 offset:19456
	global_load_lds_dwordx4 v174, s[52:53]
	s_barrier
	s_waitcnt lgkmcnt(0)
	v_mfma_f32_16x16x32_bf16 v[134:137], v[188:191], v[138:141], v[134:137]
	v_mfma_f32_16x16x32_bf16 v[130:133], v[224:227], v[138:141], v[130:133]
	v_mfma_f32_16x16x32_bf16 v[118:121], v[188:191], v[146:149], v[118:121]
	v_mfma_f32_16x16x32_bf16 v[114:117], v[224:227], v[146:149], v[114:117]
	v_mfma_f32_16x16x32_bf16 v[102:105], v[188:191], v[162:165], v[102:105]
	v_mfma_f32_16x16x32_bf16 v[98:101], v[224:227], v[162:165], v[98:101]
	v_mfma_f32_16x16x32_bf16 v[86:89], v[188:191], v[170:173], v[86:89]
	v_mfma_f32_16x16x32_bf16 v[82:85], v[224:227], v[170:173], v[82:85]
	v_mfma_f32_16x16x32_bf16 v[134:137], v[220:223], v[142:145], v[134:137]
	v_mfma_f32_16x16x32_bf16 v[130:133], v[228:231], v[142:145], v[130:133]
	v_mfma_f32_16x16x32_bf16 v[118:121], v[220:223], v[150:153], v[118:121]
	v_mfma_f32_16x16x32_bf16 v[114:117], v[228:231], v[150:153], v[114:117]
	v_mfma_f32_16x16x32_bf16 v[102:105], v[220:223], v[166:169], v[102:105]
	v_mfma_f32_16x16x32_bf16 v[98:101], v[228:231], v[166:169], v[98:101]
	v_mfma_f32_16x16x32_bf16 v[86:89], v[220:223], v[184:187], v[86:89]
	v_mfma_f32_16x16x32_bf16 v[82:85], v[228:231], v[184:187], v[82:85]
	s_barrier
	s_mov_b32 m0, s21
	ds_read_b128 v[138:141], v196 offset:16384
	ds_read_b128 v[142:145], v196 offset:17408
	ds_read_b128 v[146:149], v196 offset:18432
	ds_read_b128 v[150:153], v196 offset:19456
	ds_read_b128 v[162:165], v196 offset:20480
	ds_read_b128 v[166:169], v196 offset:21504
	ds_read_b128 v[170:173], v196 offset:22528
	global_load_lds_dwordx4 v0, s[44:45]
	s_mov_b32 m0, s50
	ds_read_b128 v[184:187], v196 offset:23552
	global_load_lds_dwordx4 v174, s[44:45]
	s_barrier
	s_waitcnt lgkmcnt(0)
	v_mfma_f32_16x16x32_bf16 v[78:81], v[58:61], v[138:141], v[78:81]
	v_mfma_f32_16x16x32_bf16 v[66:69], v[70:73], v[138:141], v[66:69]
	v_mfma_f32_16x16x32_bf16 v[46:49], v[58:61], v[146:149], v[46:49]
	v_mfma_f32_16x16x32_bf16 v[42:45], v[70:73], v[146:149], v[42:45]
	v_mfma_f32_16x16x32_bf16 v[30:33], v[58:61], v[162:165], v[30:33]
	v_mfma_f32_16x16x32_bf16 v[26:29], v[70:73], v[162:165], v[26:29]
	v_mfma_f32_16x16x32_bf16 v[14:17], v[58:61], v[170:173], v[14:17]
	v_mfma_f32_16x16x32_bf16 v[10:13], v[70:73], v[170:173], v[10:13]
	v_mfma_f32_16x16x32_bf16 v[78:81], v[62:65], v[142:145], v[78:81]
	v_mfma_f32_16x16x32_bf16 v[66:69], v[74:77], v[142:145], v[66:69]
	v_mfma_f32_16x16x32_bf16 v[46:49], v[62:65], v[150:153], v[46:49]
	v_mfma_f32_16x16x32_bf16 v[42:45], v[74:77], v[150:153], v[42:45]
	v_mfma_f32_16x16x32_bf16 v[30:33], v[62:65], v[166:169], v[30:33]
	v_mfma_f32_16x16x32_bf16 v[26:29], v[74:77], v[166:169], v[26:29]
	v_mfma_f32_16x16x32_bf16 v[14:17], v[62:65], v[184:187], v[14:17]
	v_mfma_f32_16x16x32_bf16 v[10:13], v[74:77], v[184:187], v[10:13]
	s_barrier
	s_add_u32 s100, s44, 0x80
	s_addc_u32 s101, s45, 0
	s_add_u32 s44, s44, s38
	s_addc_u32 s45, s45, 0
	s_add_u32 s52, s52, s38
	s_addc_u32 s53, s53, 0
	s_add_i32 m0, s20, 0x14000
	s_nop 0
	global_load_lds_dwordx4 v0, s[52:53]
	s_add_i32 m0, s20, 0x16000
	s_nop 0
	global_load_lds_dwordx4 v174, s[52:53]
	s_add_u32 s4, s4, 0x100
	s_addc_u32 s5, s5, 0
	s_add_u32 s89, s89, 0x100
	s_addc_u32 s90, s90, 0
	s_waitcnt vmcnt(6)
	s_barrier
; #define PG8_STAGE(bufoff, gbase, voff) do { _Pragma("unroll") for (int _i = 0; _i < 2; ++_i) \
;         __builtin_amdgcn_global_load_lds((const unsigned*)((const char*)(gbase) + (voff)[_i]), (LAS unsigned*)(lds + (bufoff) + ldsw + _i * 8192), 16, 0, 0); } while (0)
; #define PG8_LDA(dst, b, h) do { _Pragma("unroll") for (int m = 0; m < 4; ++m) _Pragma("unroll") for (int k = 0; k < 2; ++k) dst[m][k] = *(const LAS bf16x8*)(lds + PG8_SA(b, h) + aoff + m * 2048 + k * 1024); } while (0)
; #define PG8_LDB(dst, b, h) do { _Pragma("unroll") for (int n = 0; n < 2; ++n) _Pragma("unroll") for (int k = 0; k < 2; ++k) dst[n][k] = *(const LAS bf16x8*)(lds + PG8_SB(b, h) + boff + n * 2048 + k * 1024); } while (0)
; #define PG8_MMA(ai, bj, At, Bt) do { __builtin_amdgcn_s_setprio(1); _Pragma("unroll") for (int m = 0; m < 4; ++m) _Pragma("unroll") for (int n = 0; n < 2; ++n) _Pragma("unroll") for (int k = 0; k < 2; ++k) \
;         acc[ai][bj][m][n] = __builtin_amdgcn_mfma_f32_16x16x32_bf16(Bt[n][k], At[m][k], acc[ai][bj][m][n], 0, 0, 0); __builtin_amdgcn_s_setprio(0); } while (0)
; #define PG8_WAIT_V(n) asm volatile("s_waitcnt vmcnt(" #n ")" ::: "memory")
; #define PG8_WAIT_L(n) asm volatile("s_waitcnt lgkmcnt(" #n ")" ::: "memory")
; #define PG8_BAR __builtin_amdgcn_s_barrier()
; #define PG8_SCHED __builtin_amdgcn_sched_barrier(0)
; template <int MODE, class EpiT, class Sched>
; __device__ __forceinline__ void gemm_phase(LAS unsigned char* lds, const Gemm g, const Sched& S, const EpiT& E) {
;     ...
;             PG8_WAIT_V(6); PG8_BAR; PG8_MMA(1, 1, At, B1); PG8_BAR;
;             PG8_LDB(B0, 1, 0); PG8_SCHED; PG8_LDA(At, 1, 0); PG8_STAGE(PG8_SA(0, 1), a2 + hstep, voffA);
;             PG8_WAIT_L(8); PG8_BAR; PG8_WAIT_L(0); PG8_MMA(0, 0, At, B0); PG8_BAR; PG8_SCHED;
;             PG8_LDB(B1, 1, 1); PG8_STAGE(PG8_SB(1, 0), b3, voffB);
;             PG8_BAR; PG8_WAIT_L(0); PG8_MMA(0, 1, At, B1); PG8_BAR;
	v_mfma_f32_16x16x32_bf16 v[54:57], v[188:191], v[138:141], v[54:57]
	v_mfma_f32_16x16x32_bf16 v[50:53], v[224:227], v[138:141], v[50:53]
	v_mfma_f32_16x16x32_bf16 v[38:41], v[188:191], v[146:149], v[38:41]
	v_mfma_f32_16x16x32_bf16 v[34:37], v[224:227], v[146:149], v[34:37]
	v_mfma_f32_16x16x32_bf16 v[22:25], v[188:191], v[162:165], v[22:25]
	v_mfma_f32_16x16x32_bf16 v[18:21], v[224:227], v[162:165], v[18:21]
	v_mfma_f32_16x16x32_bf16 v[6:9], v[188:191], v[170:173], v[6:9]
	v_mfma_f32_16x16x32_bf16 v[2:5], v[224:227], v[170:173], v[2:5]
	v_mfma_f32_16x16x32_bf16 v[54:57], v[220:223], v[142:145], v[54:57]
	v_mfma_f32_16x16x32_bf16 v[50:53], v[228:231], v[142:145], v[50:53]
	v_mfma_f32_16x16x32_bf16 v[38:41], v[220:223], v[150:153], v[38:41]
	v_mfma_f32_16x16x32_bf16 v[34:37], v[228:231], v[150:153], v[34:37]
	v_mfma_f32_16x16x32_bf16 v[22:25], v[220:223], v[166:169], v[22:25]
	v_mfma_f32_16x16x32_bf16 v[18:21], v[228:231], v[166:169], v[18:21]
	v_mfma_f32_16x16x32_bf16 v[6:9], v[220:223], v[184:187], v[6:9]
	v_mfma_f32_16x16x32_bf16 v[2:5], v[228:231], v[184:187], v[2:5]
	s_barrier
	ds_read_b128 v[58:61], v249 offset:32768
	ds_read_b128 v[62:65], v249 offset:33792
	ds_read_b128 v[70:73], v249 offset:34816
	ds_read_b128 v[74:77], v249 offset:35840
	s_mov_b32 m0, s51
	ds_read_b128 v[138:141], v196 offset:32768
	ds_read_b128 v[142:145], v196 offset:33792
	ds_read_b128 v[146:149], v196 offset:34816
	ds_read_b128 v[150:153], v196 offset:35840
	ds_read_b128 v[162:165], v196 offset:36864
	ds_read_b128 v[166:169], v196 offset:37888
	ds_read_b128 v[170:173], v196 offset:38912
	global_load_lds_dwordx4 v0, s[44:45]
	s_mov_b32 m0, s56
	ds_read_b128 v[184:187], v196 offset:39936
	global_load_lds_dwordx4 v174, s[44:45]
	s_waitcnt lgkmcnt(8)
	s_barrier
	s_waitcnt lgkmcnt(0)
	v_mfma_f32_16x16x32_bf16 v[158:161], v[58:61], v[138:141], v[158:161]
	v_mfma_f32_16x16x32_bf16 v[154:157], v[70:73], v[138:141], v[154:157]
	v_mfma_f32_16x16x32_bf16 v[126:129], v[58:61], v[146:149], v[126:129]
	v_mfma_f32_16x16x32_bf16 v[122:125], v[70:73], v[146:149], v[122:125]
	v_mfma_f32_16x16x32_bf16 v[110:113], v[58:61], v[162:165], v[110:113]
	v_mfma_f32_16x16x32_bf16 v[106:109], v[70:73], v[162:165], v[106:109]
	v_mfma_f32_16x16x32_bf16 v[94:97], v[58:61], v[170:173], v[94:97]
	v_mfma_f32_16x16x32_bf16 v[90:93], v[70:73], v[170:173], v[90:93]
	v_mfma_f32_16x16x32_bf16 v[158:161], v[62:65], v[142:145], v[158:161]
	v_mfma_f32_16x16x32_bf16 v[154:157], v[74:77], v[142:145], v[154:157]
	v_mfma_f32_16x16x32_bf16 v[126:129], v[62:65], v[150:153], v[126:129]
	v_mfma_f32_16x16x32_bf16 v[122:125], v[74:77], v[150:153], v[122:125]
	v_mfma_f32_16x16x32_bf16 v[110:113], v[62:65], v[166:169], v[110:113]
	v_mfma_f32_16x16x32_bf16 v[106:109], v[74:77], v[166:169], v[106:109]
	v_mfma_f32_16x16x32_bf16 v[94:97], v[62:65], v[184:187], v[94:97]
	v_mfma_f32_16x16x32_bf16 v[90:93], v[74:77], v[184:187], v[90:93]
	s_barrier
	s_add_i32 m0, s20, 0x18000
	ds_read_b128 v[188:191], v249 offset:49152
	ds_read_b128 v[220:223], v249 offset:50176
	ds_read_b128 v[224:227], v249 offset:51200
	global_load_lds_dwordx4 v0, s[98:99]
	s_add_i32 m0, s20, 0x1a000
	ds_read_b128 v[228:231], v249 offset:52224
	global_load_lds_dwordx4 v174, s[98:99]
	s_barrier
	s_waitcnt lgkmcnt(0)
	v_mfma_f32_16x16x32_bf16 v[134:137], v[188:191], v[138:141], v[134:137]
	v_mfma_f32_16x16x32_bf16 v[130:133], v[224:227], v[138:141], v[130:133]
	v_mfma_f32_16x16x32_bf16 v[118:121], v[188:191], v[146:149], v[118:121]
	v_mfma_f32_16x16x32_bf16 v[114:117], v[224:227], v[146:149], v[114:117]
	v_mfma_f32_16x16x32_bf16 v[102:105], v[188:191], v[162:165], v[102:105]
	v_mfma_f32_16x16x32_bf16 v[98:101], v[224:227], v[162:165], v[98:101]
	v_mfma_f32_16x16x32_bf16 v[86:89], v[188:191], v[170:173], v[86:89]
	v_mfma_f32_16x16x32_bf16 v[82:85], v[224:227], v[170:173], v[82:85]
	v_mfma_f32_16x16x32_bf16 v[134:137], v[220:223], v[142:145], v[134:137]
	v_mfma_f32_16x16x32_bf16 v[130:133], v[228:231], v[142:145], v[130:133]
	v_mfma_f32_16x16x32_bf16 v[118:121], v[220:223], v[150:153], v[118:121]
	v_mfma_f32_16x16x32_bf16 v[114:117], v[228:231], v[150:153], v[114:117]
	v_mfma_f32_16x16x32_bf16 v[102:105], v[220:223], v[166:169], v[102:105]
	v_mfma_f32_16x16x32_bf16 v[98:101], v[228:231], v[166:169], v[98:101]
	v_mfma_f32_16x16x32_bf16 v[86:89], v[220:223], v[184:187], v[86:89]
	v_mfma_f32_16x16x32_bf16 v[82:85], v[228:231], v[184:187], v[82:85]
	s_barrier
; #define PG8_STAGE(bufoff, gbase, voff) do { _Pragma("unroll") for (int _i = 0; _i < 2; ++_i) \
;         __builtin_amdgcn_global_load_lds((const unsigned*)((const char*)(gbase) + (voff)[_i]), (LAS unsigned*)(lds + (bufoff) + ldsw + _i * 8192), 16, 0, 0); } while (0)
; #define PG8_LDA(dst, b, h) do { _Pragma("unroll") for (int m = 0; m < 4; ++m) _Pragma("unroll") for (int k = 0; k < 2; ++k) dst[m][k] = *(const LAS bf16x8*)(lds + PG8_SA(b, h) + aoff + m * 2048 + k * 1024); } while (0)
; #define PG8_MMA(ai, bj, At, Bt) do { __builtin_amdgcn_s_setprio(1); _Pragma("unroll") for (int m = 0; m < 4; ++m) _Pragma("unroll") for (int n = 0; n < 2; ++n) _Pragma("unroll") for (int k = 0; k < 2; ++k) \
;         acc[ai][bj][m][n] = __builtin_amdgcn_mfma_f32_16x16x32_bf16(Bt[n][k], At[m][k], acc[ai][bj][m][n], 0, 0, 0); __builtin_amdgcn_s_setprio(0); } while (0)
; #define PG8_WAIT_V(n) asm volatile("s_waitcnt vmcnt(" #n ")" ::: "memory")
; #define PG8_WAIT_L(n) asm volatile("s_waitcnt lgkmcnt(" #n ")" ::: "memory")
; #define PG8_BAR __builtin_amdgcn_s_barrier()
; #define PG8_SCHED __builtin_amdgcn_sched_barrier(0)
;     template <int mode> __device__ __forceinline__ void run(const f32x4 (&acc)[2][2][4][2], const Unit& u, int wr, int wc, int fr, int fq, const LAS float* sc) const {
;     ...
;             const int col0 = u.pn * BM + wc * 32 + 8 * fq;
;             float sA = 1.f, sB = 1.f;
;             if (mode == 4) scales2(u, wr, fr, fq, sA, sB);
;             f32x4 bvv[4];
; #pragma unroll
;             for (int q = 0; q < 4; ++q) bvv[q] = (mode != 4 && bias) ? *(const f32x4*)(bias + col0 + (q >> 1) * HALF + (q & 1) * 4) : (f32x4){0.f, 0.f, 0.f, 0.f};
; template <int MODE, class EpiT, class Sched>
; __device__ __forceinline__ void gemm_phase(LAS unsigned char* lds, const Gemm g, const Sched& S, const EpiT& E) {
;     ...
;             PG8_LDA(At, 1, 1); PG8_STAGE(PG8_SA(1, 0), a3, voffA);
;             PG8_BAR; PG8_WAIT_L(0); PG8_MMA(1, 0, At, B0); PG8_BAR; PG8_SCHED;
;             PG8_STAGE(PG8_SB(1, 1), b3 + hstep, voffB);
;             PG8_WAIT_V(6); PG8_BAR; PG8_MMA(1, 1, At, B1); PG8_BAR;
	s_mov_b32 m0, s61
	ds_read_b128 v[138:141], v196 offset:49152
	ds_read_b128 v[142:145], v196 offset:50176
	ds_read_b128 v[146:149], v196 offset:51200
	ds_read_b128 v[150:153], v196 offset:52224
	ds_read_b128 v[162:165], v196 offset:53248
	ds_read_b128 v[166:169], v196 offset:54272
	ds_read_b128 v[170:173], v196 offset:55296
	global_load_lds_dwordx4 v0, s[100:101]
	s_mov_b32 m0, s74
	ds_read_b128 v[184:187], v196 offset:56320
	global_load_lds_dwordx4 v174, s[100:101]
	s_barrier
	s_waitcnt lgkmcnt(0)
	v_mfma_f32_16x16x32_bf16 v[78:81], v[58:61], v[138:141], v[78:81]
	v_mfma_f32_16x16x32_bf16 v[66:69], v[70:73], v[138:141], v[66:69]
	v_mfma_f32_16x16x32_bf16 v[46:49], v[58:61], v[146:149], v[46:49]
	v_mfma_f32_16x16x32_bf16 v[42:45], v[70:73], v[146:149], v[42:45]
	v_mfma_f32_16x16x32_bf16 v[30:33], v[58:61], v[162:165], v[30:33]
	v_mfma_f32_16x16x32_bf16 v[26:29], v[70:73], v[162:165], v[26:29]
	v_mfma_f32_16x16x32_bf16 v[14:17], v[58:61], v[170:173], v[14:17]
	v_mfma_f32_16x16x32_bf16 v[10:13], v[70:73], v[170:173], v[10:13]
	v_mfma_f32_16x16x32_bf16 v[78:81], v[62:65], v[142:145], v[78:81]
	v_mfma_f32_16x16x32_bf16 v[66:69], v[74:77], v[142:145], v[66:69]
	v_mfma_f32_16x16x32_bf16 v[46:49], v[62:65], v[150:153], v[46:49]
	v_mfma_f32_16x16x32_bf16 v[42:45], v[74:77], v[150:153], v[42:45]
	v_mfma_f32_16x16x32_bf16 v[30:33], v[62:65], v[166:169], v[30:33]
	v_mfma_f32_16x16x32_bf16 v[26:29], v[74:77], v[166:169], v[26:29]
	v_mfma_f32_16x16x32_bf16 v[14:17], v[62:65], v[184:187], v[14:17]
	v_mfma_f32_16x16x32_bf16 v[10:13], v[74:77], v[184:187], v[10:13]
	s_barrier
	s_add_u32 s98, s98, s38
	s_addc_u32 s99, s99, 0
	s_add_i32 m0, s20, 0x1c000
	s_nop 0
	global_load_lds_dwordx4 v0, s[98:99]
	s_add_i32 m0, s20, 0x1e000
	s_nop 0
	global_load_lds_dwordx4 v174, s[98:99]
	s_add_u32 s100, s4, 0x80
	s_addc_u32 s101, s5, 0
	s_cmp_eq_u32 s75, vcc_lo
	s_cselect_b32 s44, s68, s100
	s_cselect_b32 s45, s69, s101
	s_cselect_b32 s53, s47, s90
	s_cselect_b32 s52, s46, s89
	s_add_u32 s98, s52, 0x80
	s_addc_u32 s99, s53, 0
	s_add_u32 s100, s4, s38
	s_addc_u32 s101, s5, 0
	s_waitcnt vmcnt(6)
	s_barrier
	v_mfma_f32_16x16x32_bf16 v[54:57], v[188:191], v[138:141], v[54:57]
	v_mfma_f32_16x16x32_bf16 v[50:53], v[224:227], v[138:141], v[50:53]
	v_mfma_f32_16x16x32_bf16 v[38:41], v[188:191], v[146:149], v[38:41]
	v_mfma_f32_16x16x32_bf16 v[34:37], v[224:227], v[146:149], v[34:37]
	v_mfma_f32_16x16x32_bf16 v[22:25], v[188:191], v[162:165], v[22:25]
	v_mfma_f32_16x16x32_bf16 v[18:21], v[224:227], v[162:165], v[18:21]
	v_mfma_f32_16x16x32_bf16 v[6:9], v[188:191], v[170:173], v[6:9]
	v_mfma_f32_16x16x32_bf16 v[2:5], v[224:227], v[170:173], v[2:5]
	v_mfma_f32_16x16x32_bf16 v[54:57], v[220:223], v[142:145], v[54:57]
	v_mfma_f32_16x16x32_bf16 v[50:53], v[228:231], v[142:145], v[50:53]
	v_mfma_f32_16x16x32_bf16 v[38:41], v[220:223], v[150:153], v[38:41]
	v_mfma_f32_16x16x32_bf16 v[34:37], v[228:231], v[150:153], v[34:37]
	v_mfma_f32_16x16x32_bf16 v[22:25], v[220:223], v[166:169], v[22:25]
	v_mfma_f32_16x16x32_bf16 v[18:21], v[228:231], v[166:169], v[18:21]
	v_mfma_f32_16x16x32_bf16 v[6:9], v[220:223], v[184:187], v[6:9]
	v_mfma_f32_16x16x32_bf16 v[2:5], v[228:231], v[184:187], v[2:5]
	s_barrier
	s_cmp_ge_u32 vcc_lo, s60
	s_cbranch_scc0 .LBB0_195
	v_lshl_or_b32 v186, s24, 8, v195
	v_ashrrev_i32_e32 v187, 31, v186
	v_mov_b32_e32 v70, 0
	v_cndmask_b32_e64 v58, 0, 1, s[78:79]
	v_lshl_add_u64 v[138:139], v[186:187], 2, s[12:13]
	v_cmp_ne_u32_e64 s[44:45], 1, v58
	s_andn2_b64 vcc, exec, s[78:79]
	v_mov_b32_e32 v74, 0
	v_mov_b32_e32 v75, v70
	v_mov_b32_e32 v184, 0
	v_mov_b32_e32 v185, v70
	s_cbranch_vccnz .LBB0_198
	global_load_dwordx4 v[74:77], v[138:139], off
	s_waitcnt vmcnt(0)
	v_mov_b32_e32 v184, v76
	v_mov_b32_e32 v185, v77
